# accumulator clearing with 64 v_mov_b64 per unit instead of 128 v_mov_b32 (6 of 7 GEMM phases), on top of cached RMS scales
# speedup vs baseline: 1.0129x; 1.0068x over previous
; template <class Epi, class Sched, bool ALIGN_EPI = false, bool SP2 = false>
; __device__ __forceinline__ void gemm_phase(PG8_LAS unsigned char* lds, const Gemm g, const Sched& S, const Epi& E) {
;     ...
;         const bool has_next = S.next(ui + 1, nxt);
;         const long nst = has_next ? -st : st; const size_t nk0 = (nst < 0) ? (size_t)(nt - 1) * kstep : (size_t)0;
;         const char* nA = has_next ? (const char*)g.A + (size_t)nxt.pm * tstep + nk0 : cA; const char* nB = has_next ? (const char*)g.Bt + (size_t)nxt.pn * tstep + nk0 : cB;
;     ...
; #pragma unroll
;         for (int a = 0; a < 2; ++a)
; #pragma unroll
;             for (int b = 0; b < 2; ++b)
; #pragma unroll
;                 for (int m = 0; m < 4; ++m)
; #pragma unroll
;                     for (int n = 0; n < 2; ++n) acc[a][b][m][n] = (f32x4){0.f, 0.f, 0.f, 0.f};
;         cur = nxt; cA = nA; cB = nB; st = nst; ++ui;
.LBB0_128:
	s_sub_u32 s34, 0, s44
	s_subb_u32 s35, 0, s45
	s_and_b64 s[36:37], s[2:3], exec
	s_cselect_b32 s47, s35, s45
	s_cselect_b32 s46, s34, s44
	s_ashr_i32 s1, s47, 31
	s_ashr_i32 s31, s30, 31
	s_and_b32 s5, s1, 0xf80
	s_lshl_b64 s[36:37], s[30:31], 20
	s_add_u32 s29, s64, s36
	s_addc_u32 s31, s65, s37
	s_add_u32 s36, s29, s5
	s_addc_u32 s37, s31, 0
	s_and_b64 s[38:39], s[2:3], exec
	s_cselect_b32 s49, s37, s43
	s_cselect_b32 s48, s36, s42
	s_ashr_i32 s29, s28, 31
	s_lshl_b64 s[38:39], s[28:29], 20
	s_add_u32 s29, s60, s38
	s_addc_u32 s31, s61, s39
	s_add_u32 s38, s29, s5
	s_addc_u32 s39, s31, 0
	s_and_b64 s[50:51], s[2:3], exec
	v_mov_b64_e32 v[0:1], 0
	s_mov_b32 s1, 0
	s_cselect_b32 s51, s39, s41
	s_cselect_b32 s50, s38, s40
	v_mov_b64_e32 v[2:3], 0
	v_mov_b64_e32 v[4:5], 0
	v_mov_b64_e32 v[6:7], 0
	v_mov_b64_e32 v[16:17], 0
	v_mov_b64_e32 v[18:19], 0
	v_mov_b64_e32 v[20:21], 0
	v_mov_b64_e32 v[22:23], 0
	v_mov_b64_e32 v[32:33], 0
	v_mov_b64_e32 v[34:35], 0
	v_mov_b64_e32 v[36:37], 0
	v_mov_b64_e32 v[38:39], 0
	v_mov_b64_e32 v[48:49], 0
	v_mov_b64_e32 v[50:51], 0
	v_mov_b64_e32 v[52:53], 0
	v_mov_b64_e32 v[54:55], 0
	v_mov_b64_e32 v[8:9], 0
	v_mov_b64_e32 v[10:11], 0
	v_mov_b64_e32 v[12:13], 0
	v_mov_b64_e32 v[14:15], 0
	v_mov_b64_e32 v[24:25], 0
	v_mov_b64_e32 v[26:27], 0
	v_mov_b64_e32 v[28:29], 0
	v_mov_b64_e32 v[30:31], 0
	v_mov_b64_e32 v[40:41], 0
	v_mov_b64_e32 v[42:43], 0
	v_mov_b64_e32 v[44:45], 0
	v_mov_b64_e32 v[46:47], 0
	v_mov_b64_e32 v[56:57], 0
	v_mov_b64_e32 v[58:59], 0
	v_mov_b64_e32 v[60:61], 0
	v_mov_b64_e32 v[62:63], 0
	v_mov_b64_e32 v[64:65], 0
	v_mov_b64_e32 v[66:67], 0
	v_mov_b64_e32 v[68:69], 0
	v_mov_b64_e32 v[70:71], 0
	v_mov_b64_e32 v[80:81], 0
	v_mov_b64_e32 v[82:83], 0
	v_mov_b64_e32 v[84:85], 0
	v_mov_b64_e32 v[86:87], 0
	v_mov_b64_e32 v[96:97], 0
	v_mov_b64_e32 v[98:99], 0
	v_mov_b64_e32 v[100:101], 0
	v_mov_b64_e32 v[102:103], 0
	v_mov_b64_e32 v[112:113], 0
	v_mov_b64_e32 v[114:115], 0
	v_mov_b64_e32 v[116:117], 0
	v_mov_b64_e32 v[118:119], 0
	v_mov_b64_e32 v[72:73], 0
	v_mov_b64_e32 v[74:75], 0
	v_mov_b64_e32 v[76:77], 0
	v_mov_b64_e32 v[78:79], 0
	v_mov_b64_e32 v[88:89], 0
	v_mov_b64_e32 v[90:91], 0
	v_mov_b64_e32 v[92:93], 0
	v_mov_b64_e32 v[94:95], 0
	v_mov_b64_e32 v[104:105], 0
	v_mov_b64_e32 v[106:107], 0
	v_mov_b64_e32 v[108:109], 0
	v_mov_b64_e32 v[110:111], 0
	v_mov_b64_e32 v[120:121], 0
	v_mov_b64_e32 v[122:123], 0
	v_mov_b64_e32 v[124:125], 0
	v_mov_b64_e32 v[126:127], 0
	s_branch .LBB0_130

; template <class Epi, class Sched, bool ALIGN_EPI = false, bool SP2 = false>
; __device__ __forceinline__ void gemm_phase(PG8_LAS unsigned char* lds, const Gemm g, const Sched& S, const Epi& E) {
;     ...
;         const bool has_next = S.next(ui + 1, nxt);
;         const long nst = has_next ? -st : st; const size_t nk0 = (nst < 0) ? (size_t)(nt - 1) * kstep : (size_t)0;
;         const char* nA = has_next ? (const char*)g.A + (size_t)nxt.pm * tstep + nk0 : cA; const char* nB = has_next ? (const char*)g.Bt + (size_t)nxt.pn * tstep + nk0 : cB;
;     ...
; #pragma unroll
;         for (int a = 0; a < 2; ++a)
; #pragma unroll
;             for (int b = 0; b < 2; ++b)
; #pragma unroll
;                 for (int m = 0; m < 4; ++m)
; #pragma unroll
;                     for (int n = 0; n < 2; ++n) acc[a][b][m][n] = (f32x4){0.f, 0.f, 0.f, 0.f};
;         cur = nxt; cA = nA; cB = nB; st = nst; ++ui;
.LBB0_323:
	s_sub_u32 s16, 0, s30
	s_subb_u32 s17, 0, s31
	s_and_b64 s[18:19], s[4:5], exec
	s_cselect_b32 s35, s17, s31
	s_cselect_b32 s34, s16, s30
	s_ashr_i32 s13, s35, 31
	s_ashr_i32 s15, s14, 31
	s_and_b32 s38, s13, 0xf80
	s_lshl_b64 s[18:19], s[14:15], 20
	s_add_u32 s13, s51, s18
	s_addc_u32 s15, s52, s19
	s_add_u32 s18, s13, s38
	s_addc_u32 s19, s15, 0
	s_and_b64 s[20:21], s[4:5], exec
	s_cselect_b32 s37, s19, s29
	s_cselect_b32 s36, s18, s28
	s_ashr_i32 s13, s12, 31
	s_lshl_b64 s[20:21], s[12:13], 20
	s_add_u32 s13, s49, s20
	s_addc_u32 s15, s50, s21
	s_add_u32 s20, s13, s38
	s_addc_u32 s21, s15, 0
	s_and_b64 s[38:39], s[4:5], exec
	s_cselect_b32 s39, s21, s27
	s_cselect_b32 s38, s20, s26
	s_add_u32 s13, s28, 0x80000
	v_mov_b64_e32 v[0:1], 0
	s_mov_b32 s23, 0
	s_addc_u32 s15, s29, 0
	s_waitcnt lgkmcnt(0)
	v_mov_b64_e32 v[2:3], 0
	v_mov_b64_e32 v[4:5], 0
	v_mov_b64_e32 v[6:7], 0
	v_mov_b64_e32 v[16:17], 0
	v_mov_b64_e32 v[18:19], 0
	v_mov_b64_e32 v[20:21], 0
	v_mov_b64_e32 v[22:23], 0
	v_mov_b64_e32 v[32:33], 0
	v_mov_b64_e32 v[34:35], 0
	v_mov_b64_e32 v[36:37], 0
	v_mov_b64_e32 v[38:39], 0
	v_mov_b64_e32 v[48:49], 0
	v_mov_b64_e32 v[50:51], 0
	v_mov_b64_e32 v[52:53], 0
	v_mov_b64_e32 v[54:55], 0
	v_mov_b64_e32 v[8:9], 0
	v_mov_b64_e32 v[10:11], 0
	v_mov_b64_e32 v[12:13], 0
	v_mov_b64_e32 v[14:15], 0
	v_mov_b64_e32 v[24:25], 0
	v_mov_b64_e32 v[26:27], 0
	v_mov_b64_e32 v[28:29], 0
	v_mov_b64_e32 v[30:31], 0
	v_mov_b64_e32 v[40:41], 0
	v_mov_b64_e32 v[42:43], 0
	v_mov_b64_e32 v[44:45], 0
	v_mov_b64_e32 v[46:47], 0
	v_mov_b64_e32 v[56:57], 0
	v_mov_b64_e32 v[58:59], 0
	v_mov_b64_e32 v[60:61], 0
	v_mov_b64_e32 v[62:63], 0
	v_mov_b64_e32 v[64:65], 0
	v_mov_b64_e32 v[66:67], 0
	v_mov_b64_e32 v[68:69], 0
	v_mov_b64_e32 v[70:71], 0
	v_mov_b64_e32 v[80:81], 0
	v_mov_b64_e32 v[82:83], 0
	v_mov_b64_e32 v[84:85], 0
	v_mov_b64_e32 v[86:87], 0
	v_mov_b64_e32 v[96:97], 0
	v_mov_b64_e32 v[98:99], 0
	v_mov_b64_e32 v[100:101], 0
	v_mov_b64_e32 v[102:103], 0
	v_mov_b64_e32 v[112:113], 0
	v_mov_b64_e32 v[114:115], 0
	v_mov_b64_e32 v[116:117], 0
	v_mov_b64_e32 v[118:119], 0
	v_mov_b64_e32 v[72:73], 0
	v_mov_b64_e32 v[74:75], 0
	v_mov_b64_e32 v[76:77], 0
	v_mov_b64_e32 v[78:79], 0
	v_mov_b64_e32 v[88:89], 0
	v_mov_b64_e32 v[90:91], 0
	v_mov_b64_e32 v[92:93], 0
	v_mov_b64_e32 v[94:95], 0
	v_mov_b64_e32 v[104:105], 0
	v_mov_b64_e32 v[106:107], 0
	v_mov_b64_e32 v[108:109], 0
	v_mov_b64_e32 v[110:111], 0
	v_mov_b64_e32 v[120:121], 0
	v_mov_b64_e32 v[122:123], 0
	v_mov_b64_e32 v[124:125], 0
	v_mov_b64_e32 v[126:127], 0
	s_branch .LBB0_325

; template <class Epi, class Sched, bool ALIGN_EPI = false, bool SP2 = false>
; __device__ __forceinline__ void gemm_phase(PG8_LAS unsigned char* lds, const Gemm g, const Sched& S, const Epi& E) {
;     ...
;         const bool has_next = S.next(ui + 1, nxt);
;         const long nst = has_next ? -st : st; const size_t nk0 = (nst < 0) ? (size_t)(nt - 1) * kstep : (size_t)0;
;         const char* nA = has_next ? (const char*)g.A + (size_t)nxt.pm * tstep + nk0 : cA; const char* nB = has_next ? (const char*)g.Bt + (size_t)nxt.pn * tstep + nk0 : cB;
;     ...
; #pragma unroll
;         for (int a = 0; a < 2; ++a)
; #pragma unroll
;             for (int b = 0; b < 2; ++b)
; #pragma unroll
;                 for (int m = 0; m < 4; ++m)
; #pragma unroll
;                     for (int n = 0; n < 2; ++n) acc[a][b][m][n] = (f32x4){0.f, 0.f, 0.f, 0.f};
;         cur = nxt; cA = nA; cB = nB; st = nst; ++ui;
.LBB0_413:
	s_sub_u32 s22, 0, s34
	s_subb_u32 s23, 0, s35
	s_and_b64 s[24:25], s[2:3], exec
	s_cselect_b32 s37, s23, s35
	s_cselect_b32 s36, s22, s34
	s_ashr_i32 s1, s37, 31
	s_ashr_i32 s21, s20, 31
	s_and_b32 s40, s1, 0xf80
	s_lshl_b64 s[24:25], s[20:21], 20
	s_add_u32 s19, s53, s24
	s_addc_u32 s21, s54, s25
	s_add_u32 s24, s19, s40
	s_addc_u32 s25, s21, 0
	s_and_b64 s[26:27], s[2:3], exec
	s_cselect_b32 s39, s25, s31
	s_cselect_b32 s38, s24, s30
	s_ashr_i32 s19, s18, 31
	s_lshl_b64 s[26:27], s[18:19], 20
	s_add_u32 s19, s4, s26
	s_addc_u32 s21, s5, s27
	s_add_u32 s26, s19, s40
	s_addc_u32 s27, s21, 0
	s_and_b64 s[40:41], s[2:3], exec
	v_mov_b64_e32 v[0:1], 0
	s_mov_b32 s1, 0
	s_cselect_b32 s41, s27, s29
	s_cselect_b32 s40, s26, s28
	v_mov_b64_e32 v[2:3], 0
	v_mov_b64_e32 v[8:9], 0
	v_mov_b64_e32 v[10:11], 0
	v_mov_b64_e32 v[16:17], 0
	v_mov_b64_e32 v[18:19], 0
	v_mov_b64_e32 v[20:21], 0
	v_mov_b64_e32 v[22:23], 0
	v_mov_b64_e32 v[32:33], 0
	v_mov_b64_e32 v[34:35], 0
	v_mov_b64_e32 v[36:37], 0
	v_mov_b64_e32 v[38:39], 0
	v_mov_b64_e32 v[48:49], 0
	v_mov_b64_e32 v[50:51], 0
	v_mov_b64_e32 v[52:53], 0
	v_mov_b64_e32 v[54:55], 0
	v_mov_b64_e32 v[4:5], 0
	v_mov_b64_e32 v[6:7], 0
	v_mov_b64_e32 v[12:13], 0
	v_mov_b64_e32 v[14:15], 0
	v_mov_b64_e32 v[24:25], 0
	v_mov_b64_e32 v[26:27], 0
	v_mov_b64_e32 v[28:29], 0
	v_mov_b64_e32 v[30:31], 0
	v_mov_b64_e32 v[40:41], 0
	v_mov_b64_e32 v[42:43], 0
	v_mov_b64_e32 v[44:45], 0
	v_mov_b64_e32 v[46:47], 0
	v_mov_b64_e32 v[56:57], 0
	v_mov_b64_e32 v[58:59], 0
	v_mov_b64_e32 v[60:61], 0
	v_mov_b64_e32 v[62:63], 0
	v_mov_b64_e32 v[64:65], 0
	v_mov_b64_e32 v[66:67], 0
	v_mov_b64_e32 v[68:69], 0
	v_mov_b64_e32 v[70:71], 0
	v_mov_b64_e32 v[80:81], 0
	v_mov_b64_e32 v[82:83], 0
	v_mov_b64_e32 v[84:85], 0
	v_mov_b64_e32 v[86:87], 0
	v_mov_b64_e32 v[96:97], 0
	v_mov_b64_e32 v[98:99], 0
	v_mov_b64_e32 v[100:101], 0
	v_mov_b64_e32 v[102:103], 0
	v_mov_b64_e32 v[112:113], 0
	v_mov_b64_e32 v[114:115], 0
	v_mov_b64_e32 v[116:117], 0
	v_mov_b64_e32 v[118:119], 0
	v_mov_b64_e32 v[72:73], 0
	v_mov_b64_e32 v[74:75], 0
	v_mov_b64_e32 v[76:77], 0
	v_mov_b64_e32 v[78:79], 0
	v_mov_b64_e32 v[88:89], 0
	v_mov_b64_e32 v[90:91], 0
	v_mov_b64_e32 v[92:93], 0
	v_mov_b64_e32 v[94:95], 0
	v_mov_b64_e32 v[104:105], 0
	v_mov_b64_e32 v[106:107], 0
	v_mov_b64_e32 v[108:109], 0
	v_mov_b64_e32 v[110:111], 0
	v_mov_b64_e32 v[120:121], 0
	v_mov_b64_e32 v[122:123], 0
	v_mov_b64_e32 v[124:125], 0
	v_mov_b64_e32 v[126:127], 0
	s_branch .LBB0_415

; template <class Epi, class Sched, bool ALIGN_EPI = false, bool SP2 = false>
; __device__ __forceinline__ void gemm_phase(PG8_LAS unsigned char* lds, const Gemm g, const Sched& S, const Epi& E) {
;     ...
;         const bool has_next = S.next(ui + 1, nxt);
;         const long nst = has_next ? -st : st; const size_t nk0 = (nst < 0) ? (size_t)(nt - 1) * kstep : (size_t)0;
;         const char* nA = has_next ? (const char*)g.A + (size_t)nxt.pm * tstep + nk0 : cA; const char* nB = has_next ? (const char*)g.Bt + (size_t)nxt.pn * tstep + nk0 : cB;
;     ...
; #pragma unroll
;         for (int a = 0; a < 2; ++a)
; #pragma unroll
;             for (int b = 0; b < 2; ++b)
; #pragma unroll
;                 for (int m = 0; m < 4; ++m)
; #pragma unroll
;                     for (int n = 0; n < 2; ++n) acc[a][b][m][n] = (f32x4){0.f, 0.f, 0.f, 0.f};
;         cur = nxt; cA = nA; cB = nB; st = nst; ++ui;
.LBB0_612:
	s_sub_u32 s20, 0, s36
	s_subb_u32 s21, 0, s37
	s_and_b64 s[22:23], s[4:5], exec
	s_cselect_b32 s39, s21, s37
	s_cselect_b32 s38, s20, s36
	s_ashr_i32 s17, s39, 31
	s_ashr_i32 s19, s18, 31
	s_and_b32 s42, s17, 0xf80
	s_lshl_b64 s[22:23], s[18:19], 20
	s_add_u32 s17, s54, s22
	s_addc_u32 s19, s55, s23
	s_add_u32 s22, s17, s42
	s_addc_u32 s23, s19, 0
	s_and_b64 s[24:25], s[4:5], exec
	s_cselect_b32 s41, s23, s35
	s_cselect_b32 s40, s22, s34
	s_ashr_i32 s17, s16, 31
	s_lshl_b64 s[24:25], s[16:17], 20
	s_add_u32 s17, s6, s24
	s_addc_u32 s19, s7, s25
	s_add_u32 s24, s17, s42
	s_addc_u32 s25, s19, 0
	s_and_b64 s[42:43], s[4:5], exec
	s_cselect_b32 s43, s25, s31
	s_cselect_b32 s42, s24, s30
	s_add_u32 s17, s34, 0x80000
	v_mov_b64_e32 v[0:1], 0
	s_mov_b32 s27, 0
	s_addc_u32 s19, s35, 0
	s_waitcnt lgkmcnt(0)
	v_mov_b64_e32 v[2:3], 0
	v_mov_b64_e32 v[4:5], 0
	v_mov_b64_e32 v[6:7], 0
	v_mov_b64_e32 v[16:17], 0
	v_mov_b64_e32 v[18:19], 0
	v_mov_b64_e32 v[20:21], 0
	v_mov_b64_e32 v[22:23], 0
	v_mov_b64_e32 v[32:33], 0
	v_mov_b64_e32 v[34:35], 0
	v_mov_b64_e32 v[36:37], 0
	v_mov_b64_e32 v[38:39], 0
	v_mov_b64_e32 v[48:49], 0
	v_mov_b64_e32 v[50:51], 0
	v_mov_b64_e32 v[52:53], 0
	v_mov_b64_e32 v[54:55], 0
	v_mov_b64_e32 v[8:9], 0
	v_mov_b64_e32 v[10:11], 0
	v_mov_b64_e32 v[12:13], 0
	v_mov_b64_e32 v[14:15], 0
	v_mov_b64_e32 v[24:25], 0
	v_mov_b64_e32 v[26:27], 0
	v_mov_b64_e32 v[28:29], 0
	v_mov_b64_e32 v[30:31], 0
	v_mov_b64_e32 v[40:41], 0
	v_mov_b64_e32 v[42:43], 0
	v_mov_b64_e32 v[44:45], 0
	v_mov_b64_e32 v[46:47], 0
	v_mov_b64_e32 v[56:57], 0
	v_mov_b64_e32 v[58:59], 0
	v_mov_b64_e32 v[60:61], 0
	v_mov_b64_e32 v[62:63], 0
	v_mov_b64_e32 v[64:65], 0
	v_mov_b64_e32 v[66:67], 0
	v_mov_b64_e32 v[68:69], 0
	v_mov_b64_e32 v[70:71], 0
	v_mov_b64_e32 v[80:81], 0
	v_mov_b64_e32 v[82:83], 0
	v_mov_b64_e32 v[84:85], 0
	v_mov_b64_e32 v[86:87], 0
	v_mov_b64_e32 v[96:97], 0
	v_mov_b64_e32 v[98:99], 0
	v_mov_b64_e32 v[100:101], 0
	v_mov_b64_e32 v[102:103], 0
	v_mov_b64_e32 v[112:113], 0
	v_mov_b64_e32 v[114:115], 0
	v_mov_b64_e32 v[116:117], 0
	v_mov_b64_e32 v[118:119], 0
	v_mov_b64_e32 v[72:73], 0
	v_mov_b64_e32 v[74:75], 0
	v_mov_b64_e32 v[76:77], 0
	v_mov_b64_e32 v[78:79], 0
	v_mov_b64_e32 v[88:89], 0
	v_mov_b64_e32 v[90:91], 0
	v_mov_b64_e32 v[92:93], 0
	v_mov_b64_e32 v[94:95], 0
	v_mov_b64_e32 v[104:105], 0
	v_mov_b64_e32 v[106:107], 0
	v_mov_b64_e32 v[108:109], 0
	v_mov_b64_e32 v[110:111], 0
	v_mov_b64_e32 v[120:121], 0
	v_mov_b64_e32 v[122:123], 0
	v_mov_b64_e32 v[124:125], 0
	v_mov_b64_e32 v[126:127], 0
	s_branch .LBB0_614

; template <class Epi, class Sched, bool ALIGN_EPI = false, bool SP2 = false>
; __device__ __forceinline__ void gemm_phase(PG8_LAS unsigned char* lds, const Gemm g, const Sched& S, const Epi& E) {
;     ...
;         const bool has_next = S.next(ui + 1, nxt);
;         const long nst = has_next ? -st : st; const size_t nk0 = (nst < 0) ? (size_t)(nt - 1) * kstep : (size_t)0;
;         const char* nA = has_next ? (const char*)g.A + (size_t)nxt.pm * tstep + nk0 : cA; const char* nB = has_next ? (const char*)g.Bt + (size_t)nxt.pn * tstep + nk0 : cB;
;     ...
; #pragma unroll
;         for (int a = 0; a < 2; ++a)
; #pragma unroll
;             for (int b = 0; b < 2; ++b)
; #pragma unroll
;                 for (int m = 0; m < 4; ++m)
; #pragma unroll
;                     for (int n = 0; n < 2; ++n) acc[a][b][m][n] = (f32x4){0.f, 0.f, 0.f, 0.f};
;         cur = nxt; cA = nA; cB = nB; st = nst; ++ui;
.LBB0_709:
	s_sub_u32 s20, 0, s30
	s_subb_u32 s21, 0, s31
	s_and_b64 s[22:23], s[4:5], exec
	s_cselect_b32 s35, s21, s31
	s_cselect_b32 s34, s20, s30
	s_ashr_i32 s17, s35, 31
	s_ashr_i32 s19, s18, 31
	s_and_b32 s38, s17, 0xf80
	s_lshl_b64 s[22:23], s[18:19], 20
	s_add_u32 s17, s53, s22
	s_addc_u32 s19, s54, s23
	s_add_u32 s22, s17, s38
	s_addc_u32 s23, s19, 0
	s_and_b64 s[24:25], s[4:5], exec
	s_cselect_b32 s37, s23, s29
	s_cselect_b32 s36, s22, s28
	s_ashr_i32 s17, s16, 31
	s_lshl_b64 s[24:25], s[16:17], 20
	s_add_u32 s17, s56, s24
	s_addc_u32 s19, s55, s25
	s_add_u32 s24, s17, s38
	s_addc_u32 s25, s19, 0
	s_and_b64 s[38:39], s[4:5], exec
	v_mov_b64_e32 v[0:1], 0
	s_mov_b32 s66, 0
	s_cselect_b32 s39, s25, s27
	s_cselect_b32 s38, s24, s26
	v_mov_b64_e32 v[2:3], 0
	v_mov_b64_e32 v[4:5], 0
	v_mov_b64_e32 v[6:7], 0
	v_mov_b64_e32 v[16:17], 0
	v_mov_b64_e32 v[18:19], 0
	v_mov_b64_e32 v[20:21], 0
	v_mov_b64_e32 v[22:23], 0
	v_mov_b64_e32 v[32:33], 0
	v_mov_b64_e32 v[34:35], 0
	v_mov_b64_e32 v[36:37], 0
	v_mov_b64_e32 v[38:39], 0
	v_mov_b64_e32 v[48:49], 0
	v_mov_b64_e32 v[50:51], 0
	v_mov_b64_e32 v[52:53], 0
	v_mov_b64_e32 v[54:55], 0
	v_mov_b64_e32 v[8:9], 0
	v_mov_b64_e32 v[10:11], 0
	v_mov_b64_e32 v[12:13], 0
	v_mov_b64_e32 v[14:15], 0
	v_mov_b64_e32 v[24:25], 0
	v_mov_b64_e32 v[26:27], 0
	v_mov_b64_e32 v[28:29], 0
	v_mov_b64_e32 v[30:31], 0
	v_mov_b64_e32 v[40:41], 0
	v_mov_b64_e32 v[42:43], 0
	v_mov_b64_e32 v[44:45], 0
	v_mov_b64_e32 v[46:47], 0
	v_mov_b64_e32 v[56:57], 0
	v_mov_b64_e32 v[58:59], 0
	v_mov_b64_e32 v[60:61], 0
	v_mov_b64_e32 v[62:63], 0
	v_mov_b64_e32 v[64:65], 0
	v_mov_b64_e32 v[66:67], 0
	v_mov_b64_e32 v[68:69], 0
	v_mov_b64_e32 v[70:71], 0
	v_mov_b64_e32 v[80:81], 0
	v_mov_b64_e32 v[82:83], 0
	v_mov_b64_e32 v[84:85], 0
	v_mov_b64_e32 v[86:87], 0
	v_mov_b64_e32 v[96:97], 0
	v_mov_b64_e32 v[98:99], 0
	v_mov_b64_e32 v[100:101], 0
	v_mov_b64_e32 v[102:103], 0
	v_mov_b64_e32 v[112:113], 0
	v_mov_b64_e32 v[114:115], 0
	v_mov_b64_e32 v[116:117], 0
	v_mov_b64_e32 v[118:119], 0
	v_mov_b64_e32 v[72:73], 0
	v_mov_b64_e32 v[74:75], 0
	v_mov_b64_e32 v[76:77], 0
	v_mov_b64_e32 v[78:79], 0
	v_mov_b64_e32 v[88:89], 0
	v_mov_b64_e32 v[90:91], 0
	v_mov_b64_e32 v[92:93], 0
	v_mov_b64_e32 v[94:95], 0
	v_mov_b64_e32 v[104:105], 0
	v_mov_b64_e32 v[106:107], 0
	v_mov_b64_e32 v[108:109], 0
	v_mov_b64_e32 v[110:111], 0
	v_mov_b64_e32 v[120:121], 0
	v_mov_b64_e32 v[122:123], 0
	v_mov_b64_e32 v[124:125], 0
	v_mov_b64_e32 v[126:127], 0
	s_branch .LBB0_711

; template <class Epi, class Sched, bool ALIGN_EPI = false, bool SP2 = false>
; __device__ __forceinline__ void gemm_phase(PG8_LAS unsigned char* lds, const Gemm g, const Sched& S, const Epi& E) {
;     ...
;         const bool has_next = S.next(ui + 1, nxt);
;         const long nst = has_next ? -st : st; const size_t nk0 = (nst < 0) ? (size_t)(nt - 1) * kstep : (size_t)0;
;         const char* nA = has_next ? (const char*)g.A + (size_t)nxt.pm * tstep + nk0 : cA; const char* nB = has_next ? (const char*)g.Bt + (size_t)nxt.pn * tstep + nk0 : cB;
;     ...
; #pragma unroll
;         for (int a = 0; a < 2; ++a)
; #pragma unroll
;             for (int b = 0; b < 2; ++b)
; #pragma unroll
;                 for (int m = 0; m < 4; ++m)
; #pragma unroll
;                     for (int n = 0; n < 2; ++n) acc[a][b][m][n] = (f32x4){0.f, 0.f, 0.f, 0.f};
;         cur = nxt; cA = nA; cB = nB; st = nst; ++ui;
.LBB0_790:
	s_sub_u32 s18, 0, s34
	s_subb_u32 s19, 0, s35
	s_and_b64 s[20:21], s[4:5], exec
	s_cselect_b32 s37, s19, s35
	s_cselect_b32 s36, s18, s34
	s_ashr_i32 s15, s37, 31
	s_ashr_i32 s17, s16, 31
	s_and_b32 s40, s15, 0x3f80
	s_lshl_b64 s[20:21], s[16:17], 22
	s_add_u32 s15, s52, s20
	s_addc_u32 s17, s53, s21
	s_add_u32 s20, s15, s40
	s_addc_u32 s21, s17, 0
	s_and_b64 s[22:23], s[4:5], exec
	s_cselect_b32 s39, s21, s31
	s_cselect_b32 s38, s20, s30
	s_ashr_i32 s15, s14, 31
	s_lshl_b64 s[22:23], s[14:15], 22
	s_add_u32 s15, s55, s22
	s_addc_u32 s17, s54, s23
	s_add_u32 s22, s15, s40
	s_addc_u32 s23, s17, 0
	s_and_b64 s[40:41], s[4:5], exec
	s_cselect_b32 s41, s23, s29
	s_cselect_b32 s40, s22, s28
	s_add_u32 s15, s30, 0x200000
	v_mov_b64_e32 v[0:1], 0
	s_mov_b32 s25, 0
	s_addc_u32 s17, s31, 0
	s_waitcnt lgkmcnt(0)
	v_mov_b64_e32 v[2:3], 0
	v_mov_b64_e32 v[4:5], 0
	v_mov_b64_e32 v[6:7], 0
	v_mov_b64_e32 v[16:17], 0
	v_mov_b64_e32 v[18:19], 0
	v_mov_b64_e32 v[20:21], 0
	v_mov_b64_e32 v[22:23], 0
	v_mov_b64_e32 v[32:33], 0
	v_mov_b64_e32 v[34:35], 0
	v_mov_b64_e32 v[36:37], 0
	v_mov_b64_e32 v[38:39], 0
	v_mov_b64_e32 v[48:49], 0
	v_mov_b64_e32 v[50:51], 0
	v_mov_b64_e32 v[52:53], 0
	v_mov_b64_e32 v[54:55], 0
	v_mov_b64_e32 v[8:9], 0
	v_mov_b64_e32 v[10:11], 0
	v_mov_b64_e32 v[12:13], 0
	v_mov_b64_e32 v[14:15], 0
	v_mov_b64_e32 v[24:25], 0
	v_mov_b64_e32 v[26:27], 0
	v_mov_b64_e32 v[28:29], 0
	v_mov_b64_e32 v[30:31], 0
	v_mov_b64_e32 v[40:41], 0
	v_mov_b64_e32 v[42:43], 0
	v_mov_b64_e32 v[44:45], 0
	v_mov_b64_e32 v[46:47], 0
	v_mov_b64_e32 v[56:57], 0
	v_mov_b64_e32 v[58:59], 0
	v_mov_b64_e32 v[60:61], 0
	v_mov_b64_e32 v[62:63], 0
	v_mov_b64_e32 v[64:65], 0
	v_mov_b64_e32 v[66:67], 0
	v_mov_b64_e32 v[68:69], 0
	v_mov_b64_e32 v[70:71], 0
	v_mov_b64_e32 v[80:81], 0
	v_mov_b64_e32 v[82:83], 0
	v_mov_b64_e32 v[84:85], 0
	v_mov_b64_e32 v[86:87], 0
	v_mov_b64_e32 v[96:97], 0
	v_mov_b64_e32 v[98:99], 0
	v_mov_b64_e32 v[100:101], 0
	v_mov_b64_e32 v[102:103], 0
	v_mov_b64_e32 v[112:113], 0
	v_mov_b64_e32 v[114:115], 0
	v_mov_b64_e32 v[116:117], 0
	v_mov_b64_e32 v[118:119], 0
	v_mov_b64_e32 v[72:73], 0
	v_mov_b64_e32 v[74:75], 0
	v_mov_b64_e32 v[76:77], 0
	v_mov_b64_e32 v[78:79], 0
	v_mov_b64_e32 v[88:89], 0
	v_mov_b64_e32 v[90:91], 0
	v_mov_b64_e32 v[92:93], 0
	v_mov_b64_e32 v[94:95], 0
	v_mov_b64_e32 v[104:105], 0
	v_mov_b64_e32 v[106:107], 0
	v_mov_b64_e32 v[108:109], 0
	v_mov_b64_e32 v[110:111], 0
	v_mov_b64_e32 v[120:121], 0
	v_mov_b64_e32 v[122:123], 0
	v_mov_b64_e32 v[124:125], 0
	v_mov_b64_e32 v[126:127], 0
	s_branch .LBB0_792
